# mixer-B loop: row sums on the matrix pipe (16x16x32 selector MFMA), coarse LDS waits, SGPR-base K/V loads, final-step pack order fixed
# speedup vs baseline: 1.0241x; 1.0241x over previous
; __device__ __forceinline__ void attnB_unit(LAS unsigned char* lds, const Args& A, int unit, const float* kng, bool do_store = true) {
;     ...
;     const short one_bits = ql == 0 ? (short)0x3F80 : (short)0;
;     const bf16x8 ones = {one_bits, one_bits, one_bits, one_bits, one_bits, one_bits, one_bits, one_bits};
;     int rb = 0;
.LBB0_324:
	s_and_b64 vcc, exec, s[6:7]
	s_cbranch_vccz .LBB0_275
	v_mov_b32_e32 v32, 0
	v_mov_b32_e32 v33, v32
	v_mov_b32_e32 v34, v32
	v_mov_b32_e32 v35, v32
	v_mov_b32_e32 v36, v32
	v_mov_b32_e32 v37, v32
	v_mov_b32_e32 v38, v32
	v_mov_b32_e32 v39, v32
	v_mov_b32_e32 v40, v32
	v_mov_b32_e32 v41, v32
	v_mov_b32_e32 v42, v32
	v_mov_b32_e32 v43, v32
	v_mov_b32_e32 v44, v32
	v_mov_b32_e32 v45, v32
	v_mov_b32_e32 v46, v32
	v_mov_b32_e32 v47, v32
	v_mov_b32_e32 v48, v32
	v_mov_b32_e32 v49, v32
	v_mov_b32_e32 v50, v32
	v_mov_b32_e32 v51, v32
	v_mov_b32_e32 v52, v32
	v_mov_b32_e32 v53, v32
	v_mov_b32_e32 v54, v32
	v_mov_b32_e32 v55, v32
	v_mov_b32_e32 v56, v32
	v_mov_b32_e32 v57, v32
	v_mov_b32_e32 v58, v32
	v_mov_b32_e32 v59, v32
	v_mov_b32_e32 v60, v32
	v_mov_b32_e32 v61, v32
	v_mov_b32_e32 v62, v32
	v_mov_b32_e32 v63, v32
	v_mov_b32_e32 v174, v32
	v_mov_b32_e32 v175, v32
	v_mov_b32_e32 v176, v32
	v_mov_b32_e32 v177, v32
	v_add_u32_e32 v172, v225, v184
	v_add_u32_e32 v173, 0xa800, v172
	v_mov_b32_e32 v182, v232
	v_add_u32_e32 v183, 0xa800, v232
	v_add_u32_e32 v186, v224, v223
	v_add_u32_e32 v187, 0xa800, v186
	v_add_u32_e32 v188, v228, v223
	v_add_u32_e32 v189, 0xa800, v188
	v_and_b32_e32 v218, 31, v217
	v_mov_b32_e32 v219, 0x3f803f80
	v_cmp_eq_u32_e32 vcc, 0, v218
	s_nop 1
	v_cndmask_b32_e32 v178, 0, v219, vcc
	v_cmp_eq_u32_e32 vcc, 17, v218
	s_nop 1
	v_cndmask_b32_e32 v178, v178, v219, vcc
	v_mov_b32_e32 v179, v178
	v_mov_b32_e32 v180, v178
	v_mov_b32_e32 v181, v178
	v_readfirstlane_b32 s4, v168
	v_readfirstlane_b32 s5, v169
	v_readfirstlane_b32 s6, v170
	v_readfirstlane_b32 s7, v171
	v_lshlrev_b32_e32 v214, 4, v217
	v_add_u32_e32 v214, 0x4000, v214
	s_mov_b32 s11, 31
	ds_read_b64_tr_b16 v[160:161], v182 offset:9216
	ds_read_b64_tr_b16 v[162:163], v182 offset:10752
	ds_read_b64_tr_b16 v[164:165], v182 offset:9280
	ds_read_b64_tr_b16 v[166:167], v182 offset:10816
	ds_read_b64_tr_b16 v[190:191], v182 offset:12288
	ds_read_b64_tr_b16 v[192:193], v182 offset:13824
	ds_read_b64_tr_b16 v[194:195], v182 offset:12352
	ds_read_b64_tr_b16 v[196:197], v182 offset:13888
	v_exp_f32_e32 v16, v16
	v_exp_f32_e32 v17, v17
	v_exp_f32_e32 v18, v18
	v_cvt_pk_bf16_f32 v238, v16, v17
	v_exp_f32_e32 v19, v19
	v_exp_f32_e32 v20, v20
	v_cvt_pk_bf16_f32 v239, v18, v19
	v_exp_f32_e32 v21, v21
	v_exp_f32_e32 v22, v22
	v_cvt_pk_bf16_f32 v240, v20, v21
	v_exp_f32_e32 v23, v23
	v_exp_f32_e32 v24, v24
	v_cvt_pk_bf16_f32 v241, v22, v23
	v_exp_f32_e32 v25, v25
	v_exp_f32_e32 v26, v26
	v_cvt_pk_bf16_f32 v242, v24, v25
	v_exp_f32_e32 v27, v27
	v_exp_f32_e32 v28, v28
	v_cvt_pk_bf16_f32 v243, v26, v27
	v_exp_f32_e32 v29, v29
	s_waitcnt lgkmcnt(0)
.Lmixb_loop:
	v_mfma_f32_32x32x16_bf16 v[32:47], v[160:163], v[238:241], v[32:47]
	ds_read_b128 v[96:99], v172 offset:21504
	ds_read_b128 v[100:103], v172 offset:21536
	ds_read_b128 v[104:107], v172 offset:21568
	ds_read_b128 v[108:111], v172 offset:21600
	v_exp_f32_e32 v30, v30
	v_cvt_pk_bf16_f32 v244, v28, v29
	v_exp_f32_e32 v31, v31
	v_mfma_f32_32x32x16_bf16 v[48:63], v[164:167], v[238:241], v[48:63]
	v_mfma_f32_16x16x32_bf16 v[174:177], v[178:181], v[238:241], v[174:177]
	ds_read_b128 v[112:115], v172 offset:26112
	ds_read_b128 v[116:119], v172 offset:26144
	ds_read_b128 v[120:123], v172 offset:26176
	ds_read_b128 v[124:127], v172 offset:26208
	v_add_u32_e32 v214, 0x2000, v214
	global_load_dwordx4 v[152:155], v214, s[4:5]
	global_load_dwordx4 v[156:159], v214, s[6:7]
	v_exp_f32_e32 v0, v0
	v_cvt_pk_bf16_f32 v245, v30, v31
	v_exp_f32_e32 v1, v1
	v_mfma_f32_32x32x16_bf16 v[32:47], v[190:193], v[242:245], v[32:47]
	ds_read_b64_tr_b16 v[198:199], v182 offset:15360
	ds_read_b64_tr_b16 v[200:201], v182 offset:16896
	v_exp_f32_e32 v2, v2
	v_cvt_pk_bf16_f32 v246, v0, v1
	v_exp_f32_e32 v3, v3
	v_mfma_f32_32x32x16_bf16 v[48:63], v[194:197], v[242:245], v[48:63]
	v_mfma_f32_16x16x32_bf16 v[174:177], v[178:181], v[242:245], v[174:177]
	ds_read_b64_tr_b16 v[202:203], v182 offset:15424
	ds_read_b64_tr_b16 v[204:205], v182 offset:16960
	v_exp_f32_e32 v4, v4
	v_cvt_pk_bf16_f32 v247, v2, v3
	v_exp_f32_e32 v5, v5
	s_waitcnt lgkmcnt(8)
	v_mfma_f32_32x32x16_bf16 v[80:95], v[96:99], v[128:131], 0
	ds_read_b64_tr_b16 v[206:207], v182 offset:18432
	ds_read_b64_tr_b16 v[208:209], v182 offset:19968
	v_exp_f32_e32 v6, v6
	v_cvt_pk_bf16_f32 v248, v4, v5
	v_exp_f32_e32 v7, v7
	v_mfma_f32_32x32x16_bf16 v[80:95], v[100:103], v[132:135], v[80:95]
	ds_read_b64_tr_b16 v[234:235], v182 offset:18496
	ds_read_b64_tr_b16 v[236:237], v182 offset:20032
	v_exp_f32_e32 v8, v8
	v_cvt_pk_bf16_f32 v249, v6, v7
	v_exp_f32_e32 v9, v9
	v_mfma_f32_32x32x16_bf16 v[80:95], v[104:107], v[136:139], v[80:95]
	ds_read_b64_tr_b16 v[160:161], v182 offset:30720
	ds_read_b64_tr_b16 v[162:163], v182 offset:32256
	v_exp_f32_e32 v10, v10
	v_cvt_pk_bf16_f32 v250, v8, v9
	v_exp_f32_e32 v11, v11
	v_mfma_f32_32x32x16_bf16 v[80:95], v[108:111], v[140:143], v[80:95]
	ds_read_b64_tr_b16 v[164:165], v182 offset:30784
	ds_read_b64_tr_b16 v[166:167], v182 offset:32320
	v_exp_f32_e32 v12, v12
	v_cvt_pk_bf16_f32 v251, v10, v11
	v_exp_f32_e32 v13, v13
	s_waitcnt lgkmcnt(12)
	v_mfma_f32_32x32x16_bf16 v[64:79], v[112:115], v[128:131], 0
	ds_read_b64_tr_b16 v[190:191], v182 offset:33792
	ds_read_b64_tr_b16 v[192:193], v182 offset:35328
	v_exp_f32_e32 v14, v14
	v_cvt_pk_bf16_f32 v252, v12, v13
	v_exp_f32_e32 v15, v15
	v_mfma_f32_32x32x16_bf16 v[64:79], v[116:119], v[132:135], v[64:79]
	ds_read_b64_tr_b16 v[194:195], v182 offset:33856
	ds_read_b64_tr_b16 v[196:197], v182 offset:35392
	v_exp_f32_e32 v80, v80
	v_cvt_pk_bf16_f32 v253, v14, v15
	v_exp_f32_e32 v81, v81
	v_mfma_f32_32x32x16_bf16 v[64:79], v[120:123], v[136:139], v[64:79]
	s_waitcnt vmcnt(2)
	ds_write_b128 v187, v[144:147]
	v_exp_f32_e32 v82, v82
	v_cvt_pk_bf16_f32 v238, v80, v81
	v_exp_f32_e32 v83, v83
	v_mfma_f32_32x32x16_bf16 v[64:79], v[124:127], v[140:143], v[64:79]
	ds_write_b128 v189, v[148:151] offset:9216
	v_exp_f32_e32 v84, v84
	v_cvt_pk_bf16_f32 v239, v82, v83
	v_exp_f32_e32 v85, v85
	s_waitcnt lgkmcnt(10)
	v_mfma_f32_32x32x16_bf16 v[32:47], v[198:201], v[246:249], v[32:47]
	v_exp_f32_e32 v86, v86
	v_cvt_pk_bf16_f32 v240, v84, v85
	v_exp_f32_e32 v87, v87
	v_mfma_f32_32x32x16_bf16 v[48:63], v[202:205], v[246:249], v[48:63]
	v_mfma_f32_16x16x32_bf16 v[174:177], v[178:181], v[246:249], v[174:177]
	v_exp_f32_e32 v88, v88
	v_cvt_pk_bf16_f32 v241, v86, v87
	v_exp_f32_e32 v89, v89
	v_mfma_f32_32x32x16_bf16 v[32:47], v[206:209], v[250:253], v[32:47]
	v_exp_f32_e32 v90, v90
	v_cvt_pk_bf16_f32 v242, v88, v89
	v_exp_f32_e32 v91, v91
	v_mfma_f32_32x32x16_bf16 v[48:63], v[234:237], v[250:253], v[48:63]
	v_mfma_f32_16x16x32_bf16 v[174:177], v[178:181], v[250:253], v[174:177]
	v_exp_f32_e32 v92, v92
	v_cvt_pk_bf16_f32 v243, v90, v91
	v_exp_f32_e32 v93, v93
	s_waitcnt lgkmcnt(0)
	s_barrier
	v_mfma_f32_32x32x16_bf16 v[32:47], v[160:163], v[238:241], v[32:47]
	ds_read_b128 v[96:99], v173
	ds_read_b128 v[100:103], v173 offset:32
	ds_read_b128 v[104:107], v173 offset:64
	ds_read_b128 v[108:111], v173 offset:96
	v_exp_f32_e32 v94, v94
	v_cvt_pk_bf16_f32 v244, v92, v93
	v_exp_f32_e32 v95, v95
	v_mfma_f32_32x32x16_bf16 v[48:63], v[164:167], v[238:241], v[48:63]
	v_mfma_f32_16x16x32_bf16 v[174:177], v[178:181], v[238:241], v[174:177]
	ds_read_b128 v[112:115], v173 offset:4608
	ds_read_b128 v[116:119], v173 offset:4640
	ds_read_b128 v[120:123], v173 offset:4672
	ds_read_b128 v[124:127], v173 offset:4704
	v_add_u32_e32 v214, 0x2000, v214
	global_load_dwordx4 v[144:147], v214, s[4:5]
	global_load_dwordx4 v[148:151], v214, s[6:7]
	v_exp_f32_e32 v64, v64
	v_cvt_pk_bf16_f32 v245, v94, v95
	v_exp_f32_e32 v65, v65
	v_mfma_f32_32x32x16_bf16 v[32:47], v[190:193], v[242:245], v[32:47]
	ds_read_b64_tr_b16 v[198:199], v182 offset:36864
	ds_read_b64_tr_b16 v[200:201], v182 offset:38400
	v_exp_f32_e32 v66, v66
	v_cvt_pk_bf16_f32 v246, v64, v65
	v_exp_f32_e32 v67, v67
	v_mfma_f32_32x32x16_bf16 v[48:63], v[194:197], v[242:245], v[48:63]
	v_mfma_f32_16x16x32_bf16 v[174:177], v[178:181], v[242:245], v[174:177]
	ds_read_b64_tr_b16 v[202:203], v182 offset:36928
	ds_read_b64_tr_b16 v[204:205], v182 offset:38464
	v_exp_f32_e32 v68, v68
	v_cvt_pk_bf16_f32 v247, v66, v67
	v_exp_f32_e32 v69, v69
	s_waitcnt lgkmcnt(8)
	v_mfma_f32_32x32x16_bf16 v[16:31], v[96:99], v[128:131], 0
	ds_read_b64_tr_b16 v[206:207], v182 offset:39936
	ds_read_b64_tr_b16 v[208:209], v182 offset:41472
	v_exp_f32_e32 v70, v70
	v_cvt_pk_bf16_f32 v248, v68, v69
	v_exp_f32_e32 v71, v71
	v_mfma_f32_32x32x16_bf16 v[16:31], v[100:103], v[132:135], v[16:31]
	ds_read_b64_tr_b16 v[234:235], v182 offset:40000
	ds_read_b64_tr_b16 v[236:237], v182 offset:41536
	v_exp_f32_e32 v72, v72
	v_cvt_pk_bf16_f32 v249, v70, v71
	v_exp_f32_e32 v73, v73
	v_mfma_f32_32x32x16_bf16 v[16:31], v[104:107], v[136:139], v[16:31]
	ds_read_b64_tr_b16 v[160:161], v183 offset:9216
	ds_read_b64_tr_b16 v[162:163], v183 offset:10752
	v_exp_f32_e32 v74, v74
	v_cvt_pk_bf16_f32 v250, v72, v73
	v_exp_f32_e32 v75, v75
	v_mfma_f32_32x32x16_bf16 v[16:31], v[108:111], v[140:143], v[16:31]
	ds_read_b64_tr_b16 v[164:165], v183 offset:9280
	ds_read_b64_tr_b16 v[166:167], v183 offset:10816
	v_exp_f32_e32 v76, v76
	v_cvt_pk_bf16_f32 v251, v74, v75
	v_exp_f32_e32 v77, v77
	s_waitcnt lgkmcnt(12)
	v_mfma_f32_32x32x16_bf16 v[0:15], v[112:115], v[128:131], 0
	ds_read_b64_tr_b16 v[190:191], v183 offset:12288
	ds_read_b64_tr_b16 v[192:193], v183 offset:13824
	v_exp_f32_e32 v78, v78
	v_cvt_pk_bf16_f32 v252, v76, v77
	v_exp_f32_e32 v79, v79
	v_mfma_f32_32x32x16_bf16 v[0:15], v[116:119], v[132:135], v[0:15]
	ds_read_b64_tr_b16 v[194:195], v183 offset:12352
	ds_read_b64_tr_b16 v[196:197], v183 offset:13888
	v_exp_f32_e32 v16, v16
	v_cvt_pk_bf16_f32 v253, v78, v79
	v_exp_f32_e32 v17, v17
	v_mfma_f32_32x32x16_bf16 v[0:15], v[120:123], v[136:139], v[0:15]
	s_waitcnt vmcnt(2)
	ds_write_b128 v187, v[152:155] offset:21504
	v_exp_f32_e32 v18, v18
	v_cvt_pk_bf16_f32 v238, v16, v17
	v_exp_f32_e32 v19, v19
	v_mfma_f32_32x32x16_bf16 v[0:15], v[124:127], v[140:143], v[0:15]
	ds_write_b128 v189, v[156:159] offset:30720
	v_exp_f32_e32 v20, v20
	v_cvt_pk_bf16_f32 v239, v18, v19
	v_exp_f32_e32 v21, v21
	s_waitcnt lgkmcnt(10)
	v_mfma_f32_32x32x16_bf16 v[32:47], v[198:201], v[246:249], v[32:47]
	v_exp_f32_e32 v22, v22
	v_cvt_pk_bf16_f32 v240, v20, v21
	v_exp_f32_e32 v23, v23
	v_mfma_f32_32x32x16_bf16 v[48:63], v[202:205], v[246:249], v[48:63]
	v_mfma_f32_16x16x32_bf16 v[174:177], v[178:181], v[246:249], v[174:177]
	v_exp_f32_e32 v24, v24
	v_cvt_pk_bf16_f32 v241, v22, v23
	v_exp_f32_e32 v25, v25
	v_mfma_f32_32x32x16_bf16 v[32:47], v[206:209], v[250:253], v[32:47]
	v_exp_f32_e32 v26, v26
	v_cvt_pk_bf16_f32 v242, v24, v25
	v_exp_f32_e32 v27, v27
	v_mfma_f32_32x32x16_bf16 v[48:63], v[234:237], v[250:253], v[48:63]
	v_mfma_f32_16x16x32_bf16 v[174:177], v[178:181], v[250:253], v[174:177]
	v_exp_f32_e32 v28, v28
	v_cvt_pk_bf16_f32 v243, v26, v27
	v_exp_f32_e32 v29, v29
	s_waitcnt lgkmcnt(0)
	s_barrier
	v_mfma_f32_32x32x16_bf16 v[32:47], v[160:163], v[238:241], v[32:47]
	ds_read_b128 v[96:99], v173 offset:21504
	ds_read_b128 v[100:103], v173 offset:21536
	ds_read_b128 v[104:107], v173 offset:21568
	ds_read_b128 v[108:111], v173 offset:21600
	v_exp_f32_e32 v30, v30
	v_cvt_pk_bf16_f32 v244, v28, v29
	v_exp_f32_e32 v31, v31
	v_mfma_f32_32x32x16_bf16 v[48:63], v[164:167], v[238:241], v[48:63]
	v_mfma_f32_16x16x32_bf16 v[174:177], v[178:181], v[238:241], v[174:177]
	ds_read_b128 v[112:115], v173 offset:26112
	ds_read_b128 v[116:119], v173 offset:26144
	ds_read_b128 v[120:123], v173 offset:26176
	ds_read_b128 v[124:127], v173 offset:26208
	v_add_u32_e32 v214, 0x2000, v214
	global_load_dwordx4 v[152:155], v214, s[4:5]
	global_load_dwordx4 v[156:159], v214, s[6:7]
	v_exp_f32_e32 v0, v0
	v_cvt_pk_bf16_f32 v245, v30, v31
	v_exp_f32_e32 v1, v1
	v_mfma_f32_32x32x16_bf16 v[32:47], v[190:193], v[242:245], v[32:47]
	ds_read_b64_tr_b16 v[198:199], v183 offset:15360
	ds_read_b64_tr_b16 v[200:201], v183 offset:16896
	v_exp_f32_e32 v2, v2
	v_cvt_pk_bf16_f32 v246, v0, v1
	v_exp_f32_e32 v3, v3
	v_mfma_f32_32x32x16_bf16 v[48:63], v[194:197], v[242:245], v[48:63]
	v_mfma_f32_16x16x32_bf16 v[174:177], v[178:181], v[242:245], v[174:177]
	ds_read_b64_tr_b16 v[202:203], v183 offset:15424
	ds_read_b64_tr_b16 v[204:205], v183 offset:16960
	v_exp_f32_e32 v4, v4
	v_cvt_pk_bf16_f32 v247, v2, v3
	v_exp_f32_e32 v5, v5
	s_waitcnt lgkmcnt(8)
	v_mfma_f32_32x32x16_bf16 v[80:95], v[96:99], v[128:131], 0
	ds_read_b64_tr_b16 v[206:207], v183 offset:18432
	ds_read_b64_tr_b16 v[208:209], v183 offset:19968
	v_exp_f32_e32 v6, v6
	v_cvt_pk_bf16_f32 v248, v4, v5
	v_exp_f32_e32 v7, v7
	v_mfma_f32_32x32x16_bf16 v[80:95], v[100:103], v[132:135], v[80:95]
	ds_read_b64_tr_b16 v[234:235], v183 offset:18496
	ds_read_b64_tr_b16 v[236:237], v183 offset:20032
	v_exp_f32_e32 v8, v8
	v_cvt_pk_bf16_f32 v249, v6, v7
	v_exp_f32_e32 v9, v9
	v_mfma_f32_32x32x16_bf16 v[80:95], v[104:107], v[136:139], v[80:95]
	ds_read_b64_tr_b16 v[160:161], v183 offset:30720
	ds_read_b64_tr_b16 v[162:163], v183 offset:32256
	v_exp_f32_e32 v10, v10
	v_cvt_pk_bf16_f32 v250, v8, v9
	v_exp_f32_e32 v11, v11
	v_mfma_f32_32x32x16_bf16 v[80:95], v[108:111], v[140:143], v[80:95]
	ds_read_b64_tr_b16 v[164:165], v183 offset:30784
	ds_read_b64_tr_b16 v[166:167], v183 offset:32320
	v_exp_f32_e32 v12, v12
	v_cvt_pk_bf16_f32 v251, v10, v11
	v_exp_f32_e32 v13, v13
	s_waitcnt lgkmcnt(12)
	v_mfma_f32_32x32x16_bf16 v[64:79], v[112:115], v[128:131], 0
	ds_read_b64_tr_b16 v[190:191], v183 offset:33792
	ds_read_b64_tr_b16 v[192:193], v183 offset:35328
	v_exp_f32_e32 v14, v14
	v_cvt_pk_bf16_f32 v252, v12, v13
	v_exp_f32_e32 v15, v15
	v_mfma_f32_32x32x16_bf16 v[64:79], v[116:119], v[132:135], v[64:79]
	ds_read_b64_tr_b16 v[194:195], v183 offset:33856
	ds_read_b64_tr_b16 v[196:197], v183 offset:35392
	v_exp_f32_e32 v80, v80
	v_cvt_pk_bf16_f32 v253, v14, v15
	v_exp_f32_e32 v81, v81
	v_mfma_f32_32x32x16_bf16 v[64:79], v[120:123], v[136:139], v[64:79]
	s_waitcnt vmcnt(2)
	ds_write_b128 v186, v[144:147]
	v_exp_f32_e32 v82, v82
	v_cvt_pk_bf16_f32 v238, v80, v81
	v_exp_f32_e32 v83, v83
	v_mfma_f32_32x32x16_bf16 v[64:79], v[124:127], v[140:143], v[64:79]
	ds_write_b128 v188, v[148:151] offset:9216
	v_exp_f32_e32 v84, v84
	v_cvt_pk_bf16_f32 v239, v82, v83
	v_exp_f32_e32 v85, v85
	s_waitcnt lgkmcnt(10)
	v_mfma_f32_32x32x16_bf16 v[32:47], v[198:201], v[246:249], v[32:47]
	v_exp_f32_e32 v86, v86
	v_cvt_pk_bf16_f32 v240, v84, v85
	v_exp_f32_e32 v87, v87
	v_mfma_f32_32x32x16_bf16 v[48:63], v[202:205], v[246:249], v[48:63]
	v_mfma_f32_16x16x32_bf16 v[174:177], v[178:181], v[246:249], v[174:177]
	v_exp_f32_e32 v88, v88
	v_cvt_pk_bf16_f32 v241, v86, v87
	v_exp_f32_e32 v89, v89
	v_mfma_f32_32x32x16_bf16 v[32:47], v[206:209], v[250:253], v[32:47]
	v_exp_f32_e32 v90, v90
	v_cvt_pk_bf16_f32 v242, v88, v89
	v_exp_f32_e32 v91, v91
	v_mfma_f32_32x32x16_bf16 v[48:63], v[234:237], v[250:253], v[48:63]
	v_mfma_f32_16x16x32_bf16 v[174:177], v[178:181], v[250:253], v[174:177]
	v_exp_f32_e32 v92, v92
	v_cvt_pk_bf16_f32 v243, v90, v91
	v_exp_f32_e32 v93, v93
	s_waitcnt lgkmcnt(0)
	s_barrier
	v_mfma_f32_32x32x16_bf16 v[32:47], v[160:163], v[238:241], v[32:47]
	ds_read_b128 v[96:99], v172
	ds_read_b128 v[100:103], v172 offset:32
	ds_read_b128 v[104:107], v172 offset:64
	ds_read_b128 v[108:111], v172 offset:96
	v_exp_f32_e32 v94, v94
	v_cvt_pk_bf16_f32 v244, v92, v93
	v_exp_f32_e32 v95, v95
	v_mfma_f32_32x32x16_bf16 v[48:63], v[164:167], v[238:241], v[48:63]
	v_mfma_f32_16x16x32_bf16 v[174:177], v[178:181], v[238:241], v[174:177]
	ds_read_b128 v[112:115], v172 offset:4608
	ds_read_b128 v[116:119], v172 offset:4640
	ds_read_b128 v[120:123], v172 offset:4672
	ds_read_b128 v[124:127], v172 offset:4704
	v_add_u32_e32 v214, 0x2000, v214
	global_load_dwordx4 v[144:147], v214, s[4:5]
	global_load_dwordx4 v[148:151], v214, s[6:7]
	v_exp_f32_e32 v64, v64
	v_cvt_pk_bf16_f32 v245, v94, v95
	v_exp_f32_e32 v65, v65
	v_mfma_f32_32x32x16_bf16 v[32:47], v[190:193], v[242:245], v[32:47]
	ds_read_b64_tr_b16 v[198:199], v183 offset:36864
	ds_read_b64_tr_b16 v[200:201], v183 offset:38400
	v_exp_f32_e32 v66, v66
	v_cvt_pk_bf16_f32 v246, v64, v65
	v_exp_f32_e32 v67, v67
	v_mfma_f32_32x32x16_bf16 v[48:63], v[194:197], v[242:245], v[48:63]
	v_mfma_f32_16x16x32_bf16 v[174:177], v[178:181], v[242:245], v[174:177]
	ds_read_b64_tr_b16 v[202:203], v183 offset:36928
	ds_read_b64_tr_b16 v[204:205], v183 offset:38464
	v_exp_f32_e32 v68, v68
	v_cvt_pk_bf16_f32 v247, v66, v67
	v_exp_f32_e32 v69, v69
	s_waitcnt lgkmcnt(8)
	v_mfma_f32_32x32x16_bf16 v[16:31], v[96:99], v[128:131], 0
	ds_read_b64_tr_b16 v[206:207], v183 offset:39936
	ds_read_b64_tr_b16 v[208:209], v183 offset:41472
	v_exp_f32_e32 v70, v70
	v_cvt_pk_bf16_f32 v248, v68, v69
	v_exp_f32_e32 v71, v71
	v_mfma_f32_32x32x16_bf16 v[16:31], v[100:103], v[132:135], v[16:31]
	ds_read_b64_tr_b16 v[234:235], v183 offset:40000
	ds_read_b64_tr_b16 v[236:237], v183 offset:41536
	v_exp_f32_e32 v72, v72
	v_cvt_pk_bf16_f32 v249, v70, v71
	v_exp_f32_e32 v73, v73
	v_mfma_f32_32x32x16_bf16 v[16:31], v[104:107], v[136:139], v[16:31]
	ds_read_b64_tr_b16 v[160:161], v182 offset:9216
	ds_read_b64_tr_b16 v[162:163], v182 offset:10752
	v_exp_f32_e32 v74, v74
	v_cvt_pk_bf16_f32 v250, v72, v73
	v_exp_f32_e32 v75, v75
	v_mfma_f32_32x32x16_bf16 v[16:31], v[108:111], v[140:143], v[16:31]
	ds_read_b64_tr_b16 v[164:165], v182 offset:9280
	ds_read_b64_tr_b16 v[166:167], v182 offset:10816
	v_exp_f32_e32 v76, v76
	v_cvt_pk_bf16_f32 v251, v74, v75
	v_exp_f32_e32 v77, v77
	s_waitcnt lgkmcnt(12)
	v_mfma_f32_32x32x16_bf16 v[0:15], v[112:115], v[128:131], 0
	ds_read_b64_tr_b16 v[190:191], v182 offset:12288
	ds_read_b64_tr_b16 v[192:193], v182 offset:13824
	v_exp_f32_e32 v78, v78
	v_cvt_pk_bf16_f32 v252, v76, v77
	v_exp_f32_e32 v79, v79
	v_mfma_f32_32x32x16_bf16 v[0:15], v[116:119], v[132:135], v[0:15]
	ds_read_b64_tr_b16 v[194:195], v182 offset:12352
	ds_read_b64_tr_b16 v[196:197], v182 offset:13888
	v_exp_f32_e32 v16, v16
	v_cvt_pk_bf16_f32 v253, v78, v79
	v_exp_f32_e32 v17, v17
	v_mfma_f32_32x32x16_bf16 v[0:15], v[120:123], v[136:139], v[0:15]
	s_waitcnt vmcnt(2)
	ds_write_b128 v186, v[152:155] offset:21504
	v_exp_f32_e32 v18, v18
	v_cvt_pk_bf16_f32 v238, v16, v17
	v_exp_f32_e32 v19, v19
	v_mfma_f32_32x32x16_bf16 v[0:15], v[124:127], v[140:143], v[0:15]
	ds_write_b128 v188, v[156:159] offset:30720
	v_exp_f32_e32 v20, v20
	v_cvt_pk_bf16_f32 v239, v18, v19
	v_exp_f32_e32 v21, v21
	s_waitcnt lgkmcnt(10)
	v_mfma_f32_32x32x16_bf16 v[32:47], v[198:201], v[246:249], v[32:47]
	v_exp_f32_e32 v22, v22
	v_cvt_pk_bf16_f32 v240, v20, v21
	v_exp_f32_e32 v23, v23
	v_mfma_f32_32x32x16_bf16 v[48:63], v[202:205], v[246:249], v[48:63]
	v_mfma_f32_16x16x32_bf16 v[174:177], v[178:181], v[246:249], v[174:177]
	v_exp_f32_e32 v24, v24
	v_cvt_pk_bf16_f32 v241, v22, v23
	v_exp_f32_e32 v25, v25
	v_mfma_f32_32x32x16_bf16 v[32:47], v[206:209], v[250:253], v[32:47]
	v_exp_f32_e32 v26, v26
	v_cvt_pk_bf16_f32 v242, v24, v25
	v_exp_f32_e32 v27, v27
	v_mfma_f32_32x32x16_bf16 v[48:63], v[234:237], v[250:253], v[48:63]
	v_mfma_f32_16x16x32_bf16 v[174:177], v[178:181], v[250:253], v[174:177]
	v_exp_f32_e32 v28, v28
	v_cvt_pk_bf16_f32 v243, v26, v27
	v_exp_f32_e32 v29, v29
	s_add_i32 s11, s11, -1
	s_cmp_lg_u32 s11, 0
	s_waitcnt lgkmcnt(0)
	s_barrier
	s_cbranch_scc1 .Lmixb_loop
	v_mfma_f32_32x32x16_bf16 v[32:47], v[160:163], v[238:241], v[32:47]
	ds_read_b128 v[96:99], v172 offset:21504
	ds_read_b128 v[100:103], v172 offset:21536
	ds_read_b128 v[104:107], v172 offset:21568
	ds_read_b128 v[108:111], v172 offset:21600
	v_exp_f32_e32 v30, v30
	v_cvt_pk_bf16_f32 v244, v28, v29
	v_exp_f32_e32 v31, v31
	v_mfma_f32_32x32x16_bf16 v[48:63], v[164:167], v[238:241], v[48:63]
	v_mfma_f32_16x16x32_bf16 v[174:177], v[178:181], v[238:241], v[174:177]
	ds_read_b128 v[112:115], v172 offset:26112
	ds_read_b128 v[116:119], v172 offset:26144
	ds_read_b128 v[120:123], v172 offset:26176
	ds_read_b128 v[124:127], v172 offset:26208
	v_add_u32_e32 v214, 0x2000, v214
	global_load_dwordx4 v[152:155], v214, s[4:5]
	global_load_dwordx4 v[156:159], v214, s[6:7]
	v_exp_f32_e32 v0, v0
	v_cvt_pk_bf16_f32 v245, v30, v31
	v_exp_f32_e32 v1, v1
	v_mfma_f32_32x32x16_bf16 v[32:47], v[190:193], v[242:245], v[32:47]
	ds_read_b64_tr_b16 v[198:199], v182 offset:15360
	ds_read_b64_tr_b16 v[200:201], v182 offset:16896
	v_exp_f32_e32 v2, v2
	v_cvt_pk_bf16_f32 v246, v0, v1
	v_exp_f32_e32 v3, v3
	v_mfma_f32_32x32x16_bf16 v[48:63], v[194:197], v[242:245], v[48:63]
	v_mfma_f32_16x16x32_bf16 v[174:177], v[178:181], v[242:245], v[174:177]
	ds_read_b64_tr_b16 v[202:203], v182 offset:15424
	ds_read_b64_tr_b16 v[204:205], v182 offset:16960
	v_exp_f32_e32 v4, v4
	v_cvt_pk_bf16_f32 v247, v2, v3
	v_exp_f32_e32 v5, v5
	s_waitcnt lgkmcnt(8)
	v_mfma_f32_32x32x16_bf16 v[80:95], v[96:99], v[128:131], 0
	ds_read_b64_tr_b16 v[206:207], v182 offset:18432
	ds_read_b64_tr_b16 v[208:209], v182 offset:19968
	v_exp_f32_e32 v6, v6
	v_cvt_pk_bf16_f32 v248, v4, v5
	v_exp_f32_e32 v7, v7
	v_mfma_f32_32x32x16_bf16 v[80:95], v[100:103], v[132:135], v[80:95]
	ds_read_b64_tr_b16 v[234:235], v182 offset:18496
	ds_read_b64_tr_b16 v[236:237], v182 offset:20032
	v_exp_f32_e32 v8, v8
	v_cvt_pk_bf16_f32 v249, v6, v7
	v_exp_f32_e32 v9, v9
	v_mfma_f32_32x32x16_bf16 v[80:95], v[104:107], v[136:139], v[80:95]
	ds_read_b64_tr_b16 v[160:161], v182 offset:30720
	ds_read_b64_tr_b16 v[162:163], v182 offset:32256
	v_exp_f32_e32 v10, v10
	v_cvt_pk_bf16_f32 v250, v8, v9
	v_exp_f32_e32 v11, v11
	v_mfma_f32_32x32x16_bf16 v[80:95], v[108:111], v[140:143], v[80:95]
	ds_read_b64_tr_b16 v[164:165], v182 offset:30784
	ds_read_b64_tr_b16 v[166:167], v182 offset:32320
	v_exp_f32_e32 v12, v12
	v_cvt_pk_bf16_f32 v251, v10, v11
	v_exp_f32_e32 v13, v13
	s_waitcnt lgkmcnt(12)
	v_mfma_f32_32x32x16_bf16 v[64:79], v[112:115], v[128:131], 0
	ds_read_b64_tr_b16 v[190:191], v182 offset:33792
	ds_read_b64_tr_b16 v[192:193], v182 offset:35328
	v_exp_f32_e32 v14, v14
	v_cvt_pk_bf16_f32 v252, v12, v13
	v_exp_f32_e32 v15, v15
	v_mfma_f32_32x32x16_bf16 v[64:79], v[116:119], v[132:135], v[64:79]
	ds_read_b64_tr_b16 v[194:195], v182 offset:33856
	ds_read_b64_tr_b16 v[196:197], v182 offset:35392
	v_exp_f32_e32 v80, v80
	v_cvt_pk_bf16_f32 v253, v14, v15
	v_exp_f32_e32 v81, v81
	v_mfma_f32_32x32x16_bf16 v[64:79], v[120:123], v[136:139], v[64:79]
	s_waitcnt vmcnt(2)
	ds_write_b128 v187, v[144:147]
	v_exp_f32_e32 v82, v82
	v_cvt_pk_bf16_f32 v238, v80, v81
	v_exp_f32_e32 v83, v83
	v_mfma_f32_32x32x16_bf16 v[64:79], v[124:127], v[140:143], v[64:79]
	ds_write_b128 v189, v[148:151] offset:9216
	v_exp_f32_e32 v84, v84
	v_cvt_pk_bf16_f32 v239, v82, v83
	v_exp_f32_e32 v85, v85
	s_waitcnt lgkmcnt(10)
	v_mfma_f32_32x32x16_bf16 v[32:47], v[198:201], v[246:249], v[32:47]
	v_exp_f32_e32 v86, v86
	v_cvt_pk_bf16_f32 v240, v84, v85
	v_exp_f32_e32 v87, v87
	v_mfma_f32_32x32x16_bf16 v[48:63], v[202:205], v[246:249], v[48:63]
	v_mfma_f32_16x16x32_bf16 v[174:177], v[178:181], v[246:249], v[174:177]
	v_exp_f32_e32 v88, v88
	v_cvt_pk_bf16_f32 v241, v86, v87
	v_exp_f32_e32 v89, v89
	v_mfma_f32_32x32x16_bf16 v[32:47], v[206:209], v[250:253], v[32:47]
	v_exp_f32_e32 v90, v90
	v_cvt_pk_bf16_f32 v242, v88, v89
	v_exp_f32_e32 v91, v91
	v_mfma_f32_32x32x16_bf16 v[48:63], v[234:237], v[250:253], v[48:63]
	v_mfma_f32_16x16x32_bf16 v[174:177], v[178:181], v[250:253], v[174:177]
	v_exp_f32_e32 v92, v92
	v_cvt_pk_bf16_f32 v243, v90, v91
	v_exp_f32_e32 v93, v93
	s_waitcnt lgkmcnt(0)
	s_barrier
	v_mfma_f32_32x32x16_bf16 v[32:47], v[160:163], v[238:241], v[32:47]
	ds_read_b128 v[96:99], v173
	ds_read_b128 v[100:103], v173 offset:32
	ds_read_b128 v[104:107], v173 offset:64
	ds_read_b128 v[108:111], v173 offset:96
	v_exp_f32_e32 v94, v94
	v_cvt_pk_bf16_f32 v244, v92, v93
	v_exp_f32_e32 v95, v95
	v_mfma_f32_32x32x16_bf16 v[48:63], v[164:167], v[238:241], v[48:63]
	v_mfma_f32_16x16x32_bf16 v[174:177], v[178:181], v[238:241], v[174:177]
	ds_read_b128 v[112:115], v173 offset:4608
	ds_read_b128 v[116:119], v173 offset:4640
	ds_read_b128 v[120:123], v173 offset:4672
	ds_read_b128 v[124:127], v173 offset:4704
	v_exp_f32_e32 v64, v64
	v_cvt_pk_bf16_f32 v245, v94, v95
	v_exp_f32_e32 v65, v65
	v_mfma_f32_32x32x16_bf16 v[32:47], v[190:193], v[242:245], v[32:47]
	ds_read_b64_tr_b16 v[198:199], v182 offset:36864
	ds_read_b64_tr_b16 v[200:201], v182 offset:38400
	v_exp_f32_e32 v66, v66
	v_cvt_pk_bf16_f32 v246, v64, v65
	v_exp_f32_e32 v67, v67
	v_mfma_f32_32x32x16_bf16 v[48:63], v[194:197], v[242:245], v[48:63]
	v_mfma_f32_16x16x32_bf16 v[174:177], v[178:181], v[242:245], v[174:177]
	ds_read_b64_tr_b16 v[202:203], v182 offset:36928
	ds_read_b64_tr_b16 v[204:205], v182 offset:38464
	v_exp_f32_e32 v68, v68
	v_cvt_pk_bf16_f32 v247, v66, v67
	v_exp_f32_e32 v69, v69
	s_waitcnt lgkmcnt(8)
	v_mfma_f32_32x32x16_bf16 v[16:31], v[96:99], v[128:131], 0
	ds_read_b64_tr_b16 v[206:207], v182 offset:39936
	ds_read_b64_tr_b16 v[208:209], v182 offset:41472
	v_exp_f32_e32 v70, v70
	v_cvt_pk_bf16_f32 v248, v68, v69
	v_exp_f32_e32 v71, v71
	v_mfma_f32_32x32x16_bf16 v[16:31], v[100:103], v[132:135], v[16:31]
	ds_read_b64_tr_b16 v[234:235], v182 offset:40000
	ds_read_b64_tr_b16 v[236:237], v182 offset:41536
	v_exp_f32_e32 v72, v72
	v_cvt_pk_bf16_f32 v249, v70, v71
	v_exp_f32_e32 v73, v73
	v_mfma_f32_32x32x16_bf16 v[16:31], v[104:107], v[136:139], v[16:31]
	ds_read_b64_tr_b16 v[160:161], v183 offset:9216
	ds_read_b64_tr_b16 v[162:163], v183 offset:10752
	v_exp_f32_e32 v74, v74
	v_cvt_pk_bf16_f32 v250, v72, v73
	v_exp_f32_e32 v75, v75
	v_mfma_f32_32x32x16_bf16 v[16:31], v[108:111], v[140:143], v[16:31]
	ds_read_b64_tr_b16 v[164:165], v183 offset:9280
	ds_read_b64_tr_b16 v[166:167], v183 offset:10816
	v_exp_f32_e32 v76, v76
	v_cvt_pk_bf16_f32 v251, v74, v75
	v_exp_f32_e32 v77, v77
	s_waitcnt lgkmcnt(12)
	v_mfma_f32_32x32x16_bf16 v[0:15], v[112:115], v[128:131], 0
	ds_read_b64_tr_b16 v[190:191], v183 offset:12288
	ds_read_b64_tr_b16 v[192:193], v183 offset:13824
	v_exp_f32_e32 v78, v78
	v_cvt_pk_bf16_f32 v252, v76, v77
	v_exp_f32_e32 v79, v79
	v_mfma_f32_32x32x16_bf16 v[0:15], v[116:119], v[132:135], v[0:15]
	ds_read_b64_tr_b16 v[194:195], v183 offset:12352
	ds_read_b64_tr_b16 v[196:197], v183 offset:13888
	v_exp_f32_e32 v16, v16
	v_cvt_pk_bf16_f32 v253, v78, v79
	v_exp_f32_e32 v17, v17
	v_mfma_f32_32x32x16_bf16 v[0:15], v[120:123], v[136:139], v[0:15]
	s_waitcnt vmcnt(0)
	ds_write_b128 v187, v[152:155] offset:21504
	v_exp_f32_e32 v18, v18
	v_cvt_pk_bf16_f32 v238, v16, v17
	v_exp_f32_e32 v19, v19
	v_mfma_f32_32x32x16_bf16 v[0:15], v[124:127], v[140:143], v[0:15]
	ds_write_b128 v189, v[156:159] offset:30720
	v_exp_f32_e32 v20, v20
	v_cvt_pk_bf16_f32 v239, v18, v19
	v_exp_f32_e32 v21, v21
	s_waitcnt lgkmcnt(10)
	v_mfma_f32_32x32x16_bf16 v[32:47], v[198:201], v[246:249], v[32:47]
	v_exp_f32_e32 v22, v22
	v_cvt_pk_bf16_f32 v240, v20, v21
	v_exp_f32_e32 v23, v23
	v_mfma_f32_32x32x16_bf16 v[48:63], v[202:205], v[246:249], v[48:63]
	v_mfma_f32_16x16x32_bf16 v[174:177], v[178:181], v[246:249], v[174:177]
	v_exp_f32_e32 v24, v24
	v_cvt_pk_bf16_f32 v241, v22, v23
	v_exp_f32_e32 v25, v25
	v_mfma_f32_32x32x16_bf16 v[32:47], v[206:209], v[250:253], v[32:47]
	v_exp_f32_e32 v26, v26
	v_cvt_pk_bf16_f32 v242, v24, v25
	v_exp_f32_e32 v27, v27
	v_mfma_f32_32x32x16_bf16 v[48:63], v[234:237], v[250:253], v[48:63]
	v_mfma_f32_16x16x32_bf16 v[174:177], v[178:181], v[250:253], v[174:177]
	v_exp_f32_e32 v28, v28
	v_cvt_pk_bf16_f32 v243, v26, v27
	v_exp_f32_e32 v29, v29
	s_waitcnt lgkmcnt(0)
	s_barrier
; __device__ __forceinline__ void attnB_unit(LAS unsigned char* lds, const Args& A, int unit, const float* kng, bool do_store = true) {
;     ...
;     l += (lp[0] + lp[1]) + (lp[2] + lp[3]);
;     l += __shfl_xor(l, 32);
	v_mfma_f32_32x32x16_bf16 v[32:47], v[160:163], v[238:241], v[32:47]
	ds_read_b128 v[96:99], v173 offset:21504
	ds_read_b128 v[100:103], v173 offset:21536
	ds_read_b128 v[104:107], v173 offset:21568
	ds_read_b128 v[108:111], v173 offset:21600
	v_exp_f32_e32 v30, v30
	v_cvt_pk_bf16_f32 v244, v28, v29
	v_exp_f32_e32 v31, v31
	v_mfma_f32_32x32x16_bf16 v[48:63], v[164:167], v[238:241], v[48:63]
	v_mfma_f32_16x16x32_bf16 v[174:177], v[178:181], v[238:241], v[174:177]
	ds_read_b128 v[112:115], v173 offset:26112
	ds_read_b128 v[116:119], v173 offset:26144
	ds_read_b128 v[120:123], v173 offset:26176
	ds_read_b128 v[124:127], v173 offset:26208
	v_exp_f32_e32 v0, v0
	v_cvt_pk_bf16_f32 v245, v30, v31
	v_exp_f32_e32 v1, v1
	v_mfma_f32_32x32x16_bf16 v[32:47], v[190:193], v[242:245], v[32:47]
	ds_read_b64_tr_b16 v[198:199], v183 offset:15360
	ds_read_b64_tr_b16 v[200:201], v183 offset:16896
	v_exp_f32_e32 v2, v2
	v_cvt_pk_bf16_f32 v246, v0, v1
	v_exp_f32_e32 v3, v3
	v_mfma_f32_32x32x16_bf16 v[48:63], v[194:197], v[242:245], v[48:63]
	v_mfma_f32_16x16x32_bf16 v[174:177], v[178:181], v[242:245], v[174:177]
	ds_read_b64_tr_b16 v[202:203], v183 offset:15424
	ds_read_b64_tr_b16 v[204:205], v183 offset:16960
	v_exp_f32_e32 v4, v4
	v_cvt_pk_bf16_f32 v247, v2, v3
	v_exp_f32_e32 v5, v5
	s_waitcnt lgkmcnt(8)
	v_mfma_f32_32x32x16_bf16 v[80:95], v[96:99], v[128:131], 0
	ds_read_b64_tr_b16 v[206:207], v183 offset:18432
	ds_read_b64_tr_b16 v[208:209], v183 offset:19968
	v_exp_f32_e32 v6, v6
	v_cvt_pk_bf16_f32 v248, v4, v5
	v_exp_f32_e32 v7, v7
	v_mfma_f32_32x32x16_bf16 v[80:95], v[100:103], v[132:135], v[80:95]
	ds_read_b64_tr_b16 v[234:235], v183 offset:18496
	ds_read_b64_tr_b16 v[236:237], v183 offset:20032
	v_exp_f32_e32 v8, v8
	v_cvt_pk_bf16_f32 v249, v6, v7
	v_exp_f32_e32 v9, v9
	v_mfma_f32_32x32x16_bf16 v[80:95], v[104:107], v[136:139], v[80:95]
	ds_read_b64_tr_b16 v[160:161], v183 offset:30720
	ds_read_b64_tr_b16 v[162:163], v183 offset:32256
	v_exp_f32_e32 v10, v10
	v_cvt_pk_bf16_f32 v250, v8, v9
	v_exp_f32_e32 v11, v11
	v_mfma_f32_32x32x16_bf16 v[80:95], v[108:111], v[140:143], v[80:95]
	ds_read_b64_tr_b16 v[164:165], v183 offset:30784
	ds_read_b64_tr_b16 v[166:167], v183 offset:32320
	v_exp_f32_e32 v12, v12
	v_cvt_pk_bf16_f32 v251, v10, v11
	v_exp_f32_e32 v13, v13
	s_waitcnt lgkmcnt(12)
	v_mfma_f32_32x32x16_bf16 v[64:79], v[112:115], v[128:131], 0
	ds_read_b64_tr_b16 v[190:191], v183 offset:33792
	ds_read_b64_tr_b16 v[192:193], v183 offset:35328
	v_exp_f32_e32 v14, v14
	v_cvt_pk_bf16_f32 v252, v12, v13
	v_exp_f32_e32 v15, v15
	v_mfma_f32_32x32x16_bf16 v[64:79], v[116:119], v[132:135], v[64:79]
	ds_read_b64_tr_b16 v[194:195], v183 offset:33856
	ds_read_b64_tr_b16 v[196:197], v183 offset:35392
	v_exp_f32_e32 v80, v80
	v_cvt_pk_bf16_f32 v253, v14, v15
	v_exp_f32_e32 v81, v81
	v_mfma_f32_32x32x16_bf16 v[64:79], v[120:123], v[136:139], v[64:79]
	v_exp_f32_e32 v82, v82
	v_cvt_pk_bf16_f32 v238, v80, v81
	v_exp_f32_e32 v83, v83
	v_mfma_f32_32x32x16_bf16 v[64:79], v[124:127], v[140:143], v[64:79]
	v_exp_f32_e32 v84, v84
	v_cvt_pk_bf16_f32 v239, v82, v83
	v_exp_f32_e32 v85, v85
	s_waitcnt lgkmcnt(8)
	v_mfma_f32_32x32x16_bf16 v[32:47], v[198:201], v[246:249], v[32:47]
	v_exp_f32_e32 v86, v86
	v_cvt_pk_bf16_f32 v240, v84, v85
	v_exp_f32_e32 v87, v87
	v_mfma_f32_32x32x16_bf16 v[48:63], v[202:205], v[246:249], v[48:63]
	v_mfma_f32_16x16x32_bf16 v[174:177], v[178:181], v[246:249], v[174:177]
	v_exp_f32_e32 v88, v88
	v_cvt_pk_bf16_f32 v241, v86, v87
	v_exp_f32_e32 v89, v89
	v_mfma_f32_32x32x16_bf16 v[32:47], v[206:209], v[250:253], v[32:47]
	v_exp_f32_e32 v90, v90
	v_cvt_pk_bf16_f32 v242, v88, v89
	v_exp_f32_e32 v91, v91
	v_mfma_f32_32x32x16_bf16 v[48:63], v[234:237], v[250:253], v[48:63]
	v_mfma_f32_16x16x32_bf16 v[174:177], v[178:181], v[250:253], v[174:177]
	v_exp_f32_e32 v92, v92
	v_cvt_pk_bf16_f32 v243, v90, v91
	v_exp_f32_e32 v93, v93
	s_waitcnt lgkmcnt(0)
	s_barrier
	v_mfma_f32_32x32x16_bf16 v[32:47], v[160:163], v[238:241], v[32:47]
	v_exp_f32_e32 v94, v94
	v_cvt_pk_bf16_f32 v244, v92, v93
	v_exp_f32_e32 v95, v95
	v_mfma_f32_32x32x16_bf16 v[48:63], v[164:167], v[238:241], v[48:63]
	v_mfma_f32_16x16x32_bf16 v[174:177], v[178:181], v[238:241], v[174:177]
	v_exp_f32_e32 v64, v64
	v_cvt_pk_bf16_f32 v245, v94, v95
	v_exp_f32_e32 v65, v65
	v_mfma_f32_32x32x16_bf16 v[32:47], v[190:193], v[242:245], v[32:47]
	ds_read_b64_tr_b16 v[198:199], v183 offset:36864
	ds_read_b64_tr_b16 v[200:201], v183 offset:38400
	v_exp_f32_e32 v66, v66
	v_cvt_pk_bf16_f32 v246, v64, v65
	v_exp_f32_e32 v67, v67
	v_mfma_f32_32x32x16_bf16 v[48:63], v[194:197], v[242:245], v[48:63]
	v_mfma_f32_16x16x32_bf16 v[174:177], v[178:181], v[242:245], v[174:177]
	ds_read_b64_tr_b16 v[202:203], v183 offset:36928
	ds_read_b64_tr_b16 v[204:205], v183 offset:38464
	v_exp_f32_e32 v68, v68
	v_cvt_pk_bf16_f32 v247, v66, v67
	v_exp_f32_e32 v69, v69
	ds_read_b64_tr_b16 v[206:207], v183 offset:39936
	ds_read_b64_tr_b16 v[208:209], v183 offset:41472
	v_exp_f32_e32 v70, v70
	v_cvt_pk_bf16_f32 v248, v68, v69
	v_exp_f32_e32 v71, v71
	ds_read_b64_tr_b16 v[234:235], v183 offset:40000
	ds_read_b64_tr_b16 v[236:237], v183 offset:41536
	v_exp_f32_e32 v72, v72
	v_cvt_pk_bf16_f32 v249, v70, v71
	v_exp_f32_e32 v73, v73
	v_exp_f32_e32 v74, v74
	v_cvt_pk_bf16_f32 v250, v72, v73
	v_exp_f32_e32 v75, v75
	v_exp_f32_e32 v76, v76
	v_cvt_pk_bf16_f32 v251, v74, v75
	v_exp_f32_e32 v77, v77
	v_exp_f32_e32 v78, v78
	v_cvt_pk_bf16_f32 v252, v76, v77
	v_exp_f32_e32 v79, v79
	s_nop 0
	v_cvt_pk_bf16_f32 v253, v78, v79
	s_waitcnt lgkmcnt(0)
	v_mfma_f32_32x32x16_bf16 v[32:47], v[198:201], v[246:249], v[32:47]
	v_mfma_f32_32x32x16_bf16 v[48:63], v[202:205], v[246:249], v[48:63]
	v_mfma_f32_16x16x32_bf16 v[174:177], v[178:181], v[246:249], v[174:177]
	v_mfma_f32_32x32x16_bf16 v[32:47], v[206:209], v[250:253], v[32:47]
	v_mfma_f32_32x32x16_bf16 v[48:63], v[234:237], v[250:253], v[48:63]
	v_mfma_f32_16x16x32_bf16 v[174:177], v[178:181], v[250:253], v[174:177]
	s_nop 7
	v_and_b32_e32 v214, 15, v217
	v_lshlrev_b32_e32 v214, 2, v214
	v_and_b32_e32 v219, 16, v217
	ds_bpermute_b32 v215, v214, v174
	ds_bpermute_b32 v218, v214, v175
	v_cmp_ne_u32_e32 vcc, 0, v219
	s_waitcnt lgkmcnt(0)
	s_nop 1
	v_cndmask_b32_e32 v174, v215, v218, vcc
	v_mul_f32_e32 v174, 0.5, v174
	v_mov_b32_e32 v175, 0
	v_mov_b32_e32 v176, 0
	v_mov_b32_e32 v177, 0
	v_mov_b32_e32 v233, 0
	s_branch .LBB0_275
